# prep: norm-gain (kscale) loads for W_up hoisted out of the per-element chain (one wait instead of 32), on top of SGU/S5 edits
# speedup vs baseline: 1.0111x; 1.0041x over previous
; #define LAS __attribute__((address_space(3)))
; __device__ __forceinline__ void transpose_store(const float (&tv)[32], int K, int N, bf16_t* WT, const float* kscale, int half, LAS float* scr, int item, int lane) {
;     const int nblk = N / 32, kb = item / nblk, nb = item % nblk, k0 = 64 * kb, n0 = 32 * nb;
; #pragma unroll
;     for (int i = 0; i < 32; ++i) { const int kk = 2 * i + (lane >> 5); float v = tv[i]; if (kscale) v *= kscale[k0 + kk]; scr[kk * 33 + (lane & 31)] = v; }
;     asm volatile("s_waitcnt lgkmcnt(0)" ::: "memory");
.LBB0_493:
	s_mul_hi_i32 s22, s81, 0x2e8ba2e9
	s_lshr_b32 s23, s22, 31
	s_ashr_i32 s96, s22, 6
	s_add_i32 s96, s96, s23
	v_cndmask_b32_e64 v80, 0, 1, s[60:61]
	v_cmp_ne_u32_e64 s[38:39], 1, v80
	s_andn2_b64 vcc, exec, s[60:61]
	s_lshl_b32 s26, s96, 6
	s_cbranch_vccnz .LBB0_495
	v_or_b32_e32 v80, s26, v66
	v_ashrrev_i32_e32 v81, 31, v80
	v_lshl_add_u64 v[80:81], v[80:81], 2, s[58:59]
	flat_load_dword v160, v[80:81]
	flat_load_dword v161, v[80:81] offset:8
	flat_load_dword v162, v[80:81] offset:16
	flat_load_dword v163, v[80:81] offset:24
	flat_load_dword v164, v[80:81] offset:32
	flat_load_dword v165, v[80:81] offset:40
	flat_load_dword v166, v[80:81] offset:48
	flat_load_dword v167, v[80:81] offset:56
	flat_load_dword v168, v[80:81] offset:64
	flat_load_dword v169, v[80:81] offset:72
	flat_load_dword v170, v[80:81] offset:80
	flat_load_dword v171, v[80:81] offset:88
	flat_load_dword v172, v[80:81] offset:96
	flat_load_dword v173, v[80:81] offset:104
	flat_load_dword v174, v[80:81] offset:112
	flat_load_dword v175, v[80:81] offset:120
	flat_load_dword v176, v[80:81] offset:128
	flat_load_dword v177, v[80:81] offset:136
	flat_load_dword v178, v[80:81] offset:144
	flat_load_dword v179, v[80:81] offset:152
	flat_load_dword v180, v[80:81] offset:160
	flat_load_dword v181, v[80:81] offset:168
	flat_load_dword v182, v[80:81] offset:176
	flat_load_dword v183, v[80:81] offset:184
	flat_load_dword v184, v[80:81] offset:192
	flat_load_dword v185, v[80:81] offset:200
	flat_load_dword v186, v[80:81] offset:208
	flat_load_dword v187, v[80:81] offset:216
	flat_load_dword v188, v[80:81] offset:224
	flat_load_dword v189, v[80:81] offset:232
	flat_load_dword v190, v[80:81] offset:240
	flat_load_dword v191, v[80:81] offset:248
	s_waitcnt vmcnt(0) lgkmcnt(0)
	v_mul_f32_e32 v0, v0, v160
	v_mul_f32_e32 v1, v1, v161
	v_mul_f32_e32 v2, v2, v162
	v_mul_f32_e32 v3, v3, v163
	v_mul_f32_e32 v4, v4, v164
	v_mul_f32_e32 v5, v5, v165
	v_mul_f32_e32 v6, v6, v166
	v_mul_f32_e32 v7, v7, v167
	v_mul_f32_e32 v8, v8, v168
	v_mul_f32_e32 v9, v9, v169
	v_mul_f32_e32 v10, v10, v170
	v_mul_f32_e32 v11, v11, v171
	v_mul_f32_e32 v12, v12, v172
	v_mul_f32_e32 v13, v13, v173
	v_mul_f32_e32 v14, v14, v174
	v_mul_f32_e32 v15, v15, v175
	v_mul_f32_e32 v16, v16, v176
	v_mul_f32_e32 v17, v17, v177
	v_mul_f32_e32 v18, v18, v178
	v_mul_f32_e32 v19, v19, v179
	v_mul_f32_e32 v20, v20, v180
	v_mul_f32_e32 v21, v21, v181
	v_mul_f32_e32 v22, v22, v182
	v_mul_f32_e32 v23, v23, v183
	v_mul_f32_e32 v24, v24, v184
	v_mul_f32_e32 v25, v25, v185
	v_mul_f32_e32 v26, v26, v186
	v_mul_f32_e32 v27, v27, v187
	v_mul_f32_e32 v28, v28, v188
	v_mul_f32_e32 v29, v29, v189
	v_mul_f32_e32 v30, v30, v190
	v_mul_f32_e32 v31, v31, v191
.LBB0_495:
	s_and_b64 vcc, exec, s[38:39]
	s_waitcnt vmcnt(0) lgkmcnt(0)
	ds_write_b32 v104, v0
	s_cbranch_vccnz .LBB0_497
	s_ashr_i32 s27, s26, 31
.LBB0_497:
	v_add_u32_e32 v0, v103, v105
	s_and_b64 vcc, exec, s[38:39]
	ds_write_b32 v0, v1
	s_cbranch_vccnz .LBB0_499
	s_ashr_i32 s27, s26, 31
.LBB0_499:
	v_add_u32_e32 v0, v103, v106
	s_and_b64 vcc, exec, s[38:39]
	ds_write_b32 v0, v2
	s_cbranch_vccnz .LBB0_501
	s_ashr_i32 s27, s26, 31
.LBB0_501:
	v_add_u32_e32 v0, v103, v107
	s_and_b64 vcc, exec, s[38:39]
	ds_write_b32 v0, v3
	s_cbranch_vccnz .LBB0_503
	s_ashr_i32 s27, s26, 31
.LBB0_503:
	v_add_u32_e32 v0, v103, v108
	s_and_b64 vcc, exec, s[38:39]
	ds_write_b32 v0, v4
	s_cbranch_vccnz .LBB0_505
	s_ashr_i32 s27, s26, 31
.LBB0_505:
	v_add_u32_e32 v0, v103, v109
	s_and_b64 vcc, exec, s[38:39]
	ds_write_b32 v0, v5
	s_cbranch_vccnz .LBB0_507
	s_ashr_i32 s27, s26, 31
; #define LAS __attribute__((address_space(3)))
; __device__ __forceinline__ void transpose_store(const float (&tv)[32], int K, int N, bf16_t* WT, const float* kscale, int half, LAS float* scr, int item, int lane) {
;     const int nblk = N / 32, kb = item / nblk, nb = item % nblk, k0 = 64 * kb, n0 = 32 * nb;
; #pragma unroll
;     for (int i = 0; i < 32; ++i) { const int kk = 2 * i + (lane >> 5); float v = tv[i]; if (kscale) v *= kscale[k0 + kk]; scr[kk * 33 + (lane & 31)] = v; }
;     asm volatile("s_waitcnt lgkmcnt(0)" ::: "memory");
.LBB0_507:
	v_add_u32_e32 v0, v103, v110
	s_and_b64 vcc, exec, s[38:39]
	ds_write_b32 v0, v6
	s_cbranch_vccnz .LBB0_509
	s_ashr_i32 s27, s26, 31
.LBB0_509:
	v_add_u32_e32 v0, v103, v111
	s_and_b64 vcc, exec, s[38:39]
	ds_write_b32 v0, v7
	s_cbranch_vccnz .LBB0_511
	s_ashr_i32 s27, s26, 31
.LBB0_511:
	v_add_u32_e32 v0, v103, v112
	s_and_b64 vcc, exec, s[38:39]
	ds_write_b32 v0, v8
	s_cbranch_vccnz .LBB0_513
	s_ashr_i32 s27, s26, 31
.LBB0_513:
	v_add_u32_e32 v0, v103, v113
	s_and_b64 vcc, exec, s[38:39]
	ds_write_b32 v0, v9
	s_cbranch_vccnz .LBB0_515
	s_ashr_i32 s27, s26, 31
.LBB0_515:
	v_add_u32_e32 v0, v103, v114
	s_and_b64 vcc, exec, s[38:39]
	ds_write_b32 v0, v10
	s_cbranch_vccnz .LBB0_517
	s_ashr_i32 s27, s26, 31
.LBB0_517:
	v_add_u32_e32 v0, v103, v115
	s_and_b64 vcc, exec, s[38:39]
	ds_write_b32 v0, v11
	s_cbranch_vccnz .LBB0_519
	s_ashr_i32 s27, s26, 31
.LBB0_519:
	v_add_u32_e32 v0, v103, v116
	s_and_b64 vcc, exec, s[38:39]
	ds_write_b32 v0, v12
	s_cbranch_vccnz .LBB0_521
	s_ashr_i32 s27, s26, 31
.LBB0_521:
	v_add_u32_e32 v0, v103, v117
	s_and_b64 vcc, exec, s[38:39]
	ds_write_b32 v0, v13
	s_cbranch_vccnz .LBB0_523
	s_ashr_i32 s27, s26, 31
.LBB0_523:
	v_add_u32_e32 v0, v103, v118
	s_and_b64 vcc, exec, s[38:39]
	ds_write_b32 v0, v14
	s_cbranch_vccnz .LBB0_525
	s_ashr_i32 s27, s26, 31
.LBB0_525:
	v_add_u32_e32 v0, v103, v119
	s_and_b64 vcc, exec, s[38:39]
	ds_write_b32 v0, v15
	s_cbranch_vccnz .LBB0_527
	s_ashr_i32 s27, s26, 31
.LBB0_527:
	v_add_u32_e32 v0, v103, v120
	s_and_b64 vcc, exec, s[38:39]
	ds_write_b32 v0, v16
	s_cbranch_vccnz .LBB0_529
	s_ashr_i32 s27, s26, 31
.LBB0_529:
	v_add_u32_e32 v0, v103, v121
	s_and_b64 vcc, exec, s[38:39]
	ds_write_b32 v0, v17
	s_cbranch_vccnz .LBB0_531
	s_ashr_i32 s27, s26, 31
.LBB0_531:
	v_add_u32_e32 v0, v103, v122
	s_and_b64 vcc, exec, s[38:39]
	ds_write_b32 v0, v18
	s_cbranch_vccnz .LBB0_533
	s_ashr_i32 s27, s26, 31
.LBB0_533:
	v_add_u32_e32 v0, v103, v123
	s_and_b64 vcc, exec, s[38:39]
	ds_write_b32 v0, v19
	s_cbranch_vccnz .LBB0_535
	s_ashr_i32 s27, s26, 31
.LBB0_535:
	s_and_b64 vcc, exec, s[38:39]
	ds_write_b32 v0, v20 offset:264
	s_cbranch_vccnz .LBB0_537
	s_ashr_i32 s27, s26, 31
.LBB0_537:
	s_and_b64 vcc, exec, s[38:39]
	ds_write_b32 v0, v21 offset:528
	s_cbranch_vccnz .LBB0_539
	s_ashr_i32 s27, s26, 31
.LBB0_539:
	s_and_b64 vcc, exec, s[38:39]
	ds_write_b32 v0, v22 offset:792
	s_cbranch_vccnz .LBB0_541
	s_ashr_i32 s27, s26, 31
.LBB0_541:
	s_and_b64 vcc, exec, s[38:39]
	ds_write_b32 v0, v23 offset:1056
	s_cbranch_vccnz .LBB0_543
	s_ashr_i32 s27, s26, 31
.LBB0_543:
	s_and_b64 vcc, exec, s[38:39]
	ds_write_b32 v0, v24 offset:1320
	s_cbranch_vccnz .LBB0_545
	s_ashr_i32 s27, s26, 31
.LBB0_545:
	s_and_b64 vcc, exec, s[38:39]
	ds_write_b32 v0, v25 offset:1584
	s_cbranch_vccnz .LBB0_547
	s_ashr_i32 s27, s26, 31
.LBB0_547:
	s_and_b64 vcc, exec, s[38:39]
	ds_write_b32 v0, v26 offset:1848
	s_cbranch_vccnz .LBB0_549
	s_ashr_i32 s27, s26, 31
.LBB0_549:
	s_and_b64 vcc, exec, s[38:39]
	ds_write_b32 v0, v27 offset:2112
	s_cbranch_vccnz .LBB0_551
	s_ashr_i32 s27, s26, 31
.LBB0_551:
	s_and_b64 vcc, exec, s[38:39]
	ds_write_b32 v0, v28 offset:2376
	s_cbranch_vccnz .LBB0_553
	s_ashr_i32 s27, s26, 31
.LBB0_553:
	s_and_b64 vcc, exec, s[38:39]
	ds_write_b32 v0, v29 offset:2640
	s_cbranch_vccnz .LBB0_555
	s_ashr_i32 s27, s26, 31
.LBB0_555:
	s_and_b64 vcc, exec, s[60:61]
	ds_write_b32 v0, v30 offset:2904
	s_cbranch_vccz .LBB0_557
	s_ashr_i32 s27, s26, 31
	v_mov_b32_e32 v1, v31
	s_cbranch_execnz .LBB0_490
	s_branch .LBB0_489
